# dilated attention: row max over the 80 scores with two v_max3 chains (40 VALU) instead of canonicalising v_max pairs (140 VALU)
# speedup vs baseline: 1.0067x; 1.0067x over previous
; __device__ __forceinline__ float shx(float v, int m, int lane) { return __builtin_bit_cast(float, __builtin_amdgcn_ds_bpermute((lane ^ m) << 2, __builtin_bit_cast(int, v))); }
; __device__ __forceinline__ int crow(int r,int hi){return (r&3)+8*(r>>2)+4*hi;}
; __device__ __forceinline__ float shx(float v, int m, int lane) { return __builtin_bit_cast(float, __builtin_amdgcn_ds_bpermute((lane ^ m) << 2, __builtin_bit_cast(int, v))); }
; __device__ __forceinline__ int crow(int reg, int h) { return (reg & 3) + 8 * (reg >> 2) + 4 * h; }
; __device__ __forceinline__ void phase(LAS unsigned char* L, const u16* __restrict__ QKV, u16* OBg0, u16* OBg1, u16* OBg2, float* LSE, int first, int stride, const int tid) {
;     ...
;         float m = -INFINITY;
;         const int kneg = 128 - i0 - 32 * w;
; #pragma unroll
;         for (int i = 0; i < 16; ++i) { const int c = crow(i, h);
;             X[0][i] = (c >= r && c >= kneg) ? X[0][i] : -INFINITY; X[4][i] = (c <= r) ? X[4][i] : -INFINITY; }
;         if (kneg > 32) {
; #pragma unroll
;             for (int kb = 1; kb < 4; ++kb)
; #pragma unroll
;                 for (int i = 0; i < 16; ++i) X[kb][i] = (32 * kb + crow(i, h) >= kneg) ? X[kb][i] : -INFINITY;
;         }
; #pragma unroll
;         for (int kb = 0; kb < 5; ++kb)
; #pragma unroll
;             for (int i = 0; i < 16; i += 2) m = fmaxf(m, fmaxf(X[kb][i], X[kb][i + 1]));
;         m = fmaxf(m, shx(m, 32, lane));
;         float l = 0.f;
; #pragma unroll
;         for (int kb = 0; kb < 5; ++kb)
; #pragma unroll
;             for (int i = 0; i < 16; ++i) { X[kb][i] = __builtin_amdgcn_exp2f(X[kb][i] - m); l += X[kb][i]; }
;         l += shx(l, 32, lane);
.LBB0_482:
	v_cmp_gt_i32_e32 vcc, s13, v170
	s_or_b64 vcc, s[2:3], vcc
	s_nop 8
	v_cndmask_b32_e64 v146, v248, v67, s[2:3]
	v_cndmask_b32_e32 v150, v50, v248, vcc
	v_cmp_gt_i32_e32 vcc, s13, v172
	s_or_b64 vcc, s[76:77], vcc
	v_cndmask_b32_e64 v67, v71, v248, s[30:31]
	v_cndmask_b32_e32 v151, v51, v248, vcc
	v_cmp_gt_i32_e32 vcc, s13, v173
	s_or_b64 vcc, s[16:17], vcc
	v_cndmask_b32_e64 v147, v68, v248, s[18:19]
	v_cndmask_b32_e32 v152, v52, v248, vcc
	v_cmp_gt_i32_e32 vcc, s13, v174
	s_or_b64 vcc, s[20:21], vcc
	v_cndmask_b32_e64 v68, v72, v248, s[36:37]
	v_cndmask_b32_e32 v153, v53, v248, vcc
	v_cmp_gt_i32_e32 vcc, s13, v175
	s_or_b64 vcc, s[24:25], vcc
	v_cndmask_b32_e64 v148, v69, v248, s[22:23]
	v_cndmask_b32_e32 v154, v54, v248, vcc
	v_cmp_gt_i32_e32 vcc, s13, v176
	s_or_b64 vcc, s[28:29], vcc
	v_cndmask_b32_e64 v69, v73, v248, s[40:41]
	v_cndmask_b32_e32 v155, v55, v248, vcc
	v_cmp_gt_i32_e32 vcc, s13, v177
	s_or_b64 vcc, s[34:35], vcc
	v_readlane_b32 s50, v254, 12
	v_cndmask_b32_e32 v71, v56, v248, vcc
	v_cmp_gt_i32_e32 vcc, s13, v178
	s_or_b64 vcc, s[38:39], vcc
	v_readlane_b32 s51, v254, 13
	v_cndmask_b32_e32 v72, v57, v248, vcc
	v_cmp_gt_i32_e32 vcc, s13, v179
	s_or_b64 vcc, s[42:43], vcc
	v_cndmask_b32_e64 v149, v66, v248, s[50:51]
	v_cndmask_b32_e32 v73, v58, v248, vcc
	v_cmp_gt_i32_e32 vcc, s13, v180
	s_or_b64 vcc, s[46:47], vcc
	v_readlane_b32 s50, v254, 18
	v_cndmask_b32_e32 v59, v59, v248, vcc
	v_cmp_gt_i32_e32 vcc, s13, v181
	s_or_b64 vcc, s[4:5], vcc
	v_readlane_b32 s51, v254, 19
	v_cndmask_b32_e32 v60, v60, v248, vcc
	v_cmp_gt_i32_e32 vcc, s13, v182
	s_or_b64 vcc, s[54:55], vcc
	v_cndmask_b32_e32 v61, v61, v248, vcc
	v_cmp_gt_i32_e32 vcc, s13, v183
	s_or_b64 vcc, s[58:59], vcc
	v_cndmask_b32_e32 v62, v62, v248, vcc
	v_cmp_gt_i32_e32 vcc, s13, v184
	s_or_b64 vcc, s[62:63], vcc
	v_cndmask_b32_e64 v66, v74, v248, s[44:45]
	v_cndmask_b32_e32 v63, v63, v248, vcc
	v_cmp_gt_i32_e32 vcc, s13, v185
	s_or_b64 vcc, s[50:51], vcc
	v_cndmask_b32_e32 v64, v64, v248, vcc
	v_cmp_gt_i32_e32 vcc, s13, v186
	s_mov_b32 s13, 0xff800000
	v_cndmask_b32_e64 v56, v75, v248, s[48:49]
	v_readlane_b32 s50, v254, 16
	s_nop 1
	v_readlane_b32 s51, v254, 17
	s_nop 1
	v_cndmask_b32_e64 v53, v80, v248, s[50:51]
	v_readlane_b32 s50, v254, 20
	s_nop 1
	v_readlane_b32 s51, v254, 21
	s_nop 1
	s_or_b64 vcc, s[50:51], vcc
	v_cndmask_b32_e32 v65, v65, v248, vcc
	v_cndmask_b32_e64 v70, v70, v248, s[26:27]
	v_cndmask_b32_e64 v57, v76, v248, s[52:53]
	v_cndmask_b32_e64 v58, v77, v248, s[56:57]
	v_readlane_b32 s50, v254, 22
	v_cndmask_b32_e64 v55, v78, v248, s[60:61]
	v_cndmask_b32_e64 v51, v79, v248, s[64:65]
	v_readlane_b32 s51, v254, 23
	s_nop 1
	v_cndmask_b32_e64 v54, v81, v248, s[50:51]
	v_max3_f32 v52, v151, v150, v153
	v_max3_f32 v74, v152, v155, v154
	v_max3_f32 v52, v52, v72, v71
	v_max3_f32 v74, v74, v59, v73
	v_max3_f32 v52, v52, v61, v60
	v_max3_f32 v74, v74, v63, v62
	v_max3_f32 v52, v52, v65, v64
	v_max3_f32 v74, v74, v35, v34
	v_max3_f32 v52, v52, v37, v36
	v_max3_f32 v74, v74, v39, v38
	v_max3_f32 v52, v52, v41, v40
	v_max3_f32 v74, v74, v43, v42
	v_max3_f32 v52, v52, v45, v44
	v_max3_f32 v74, v74, v47, v46
	v_max3_f32 v52, v52, v49, v48
	v_max3_f32 v74, v74, v19, v18
	v_max3_f32 v52, v52, v21, v20
	v_max3_f32 v74, v74, v23, v22
	v_max3_f32 v52, v52, v25, v24
	v_max3_f32 v74, v74, v27, v26
	v_max3_f32 v52, v52, v29, v28
	v_max3_f32 v74, v74, v31, v30
	v_max3_f32 v52, v52, v33, v32
	v_max3_f32 v74, v74, v3, v2
	v_max3_f32 v52, v52, v5, v4
	v_max3_f32 v74, v74, v7, v6
	v_max3_f32 v52, v52, v9, v8
	v_max3_f32 v74, v74, v11, v10
	v_max3_f32 v52, v52, v13, v12
	v_max3_f32 v74, v74, v15, v14
	v_max3_f32 v52, v52, v17, v16
	v_max3_f32 v74, v74, v146, v149
	v_max3_f32 v52, v52, v148, v147
	v_max3_f32 v74, v74, v67, v70
	v_max3_f32 v52, v52, v69, v68
	v_max3_f32 v74, v74, v56, v66
	v_max3_f32 v52, v52, v58, v57
	v_max3_f32 v74, v74, v51, v55
	v_max3_f32 v52, v52, v54, v53
	v_max_f32_e32 v52, v52, v74
	ds_bpermute_b32 v74, v171, v52
	s_ashr_i32 vcc_lo, s68, 4
	s_sub_i32 s14, 5, s9
	v_or_b32_e32 v50, s12, v162
	s_ashr_i32 vcc_hi, vcc_lo, 31
	s_waitcnt lgkmcnt(0)
	v_max_f32_e32 v74, v74, v74
	v_max_f32_e32 v52, v52, v74
	v_sub_f32_e32 v74, v150, v52
	v_exp_f32_e32 v74, v74
	v_sub_f32_e32 v75, v151, v52
	v_exp_f32_e32 v75, v75
	v_sub_f32_e32 v76, v152, v52
	v_exp_f32_e32 v76, v76
	v_sub_f32_e32 v78, v153, v52
	v_exp_f32_e32 v78, v78
	v_sub_f32_e32 v79, v154, v52
	v_add_f32_e32 v77, 0, v74
	v_exp_f32_e32 v79, v79
	v_sub_f32_e32 v80, v155, v52
	v_add_f32_e32 v77, v75, v77
	v_exp_f32_e32 v80, v80
	v_sub_f32_e32 v71, v71, v52
	v_add_f32_e32 v77, v76, v77
	v_exp_f32_e32 v71, v71
	v_sub_f32_e32 v72, v72, v52
	v_add_f32_e32 v77, v78, v77
	v_exp_f32_e32 v72, v72
	v_sub_f32_e32 v73, v73, v52
	v_add_f32_e32 v77, v79, v77
	v_exp_f32_e32 v73, v73
	v_sub_f32_e32 v59, v59, v52
	v_add_f32_e32 v77, v80, v77
	v_exp_f32_e32 v59, v59
	v_sub_f32_e32 v60, v60, v52
	v_add_f32_e32 v77, v71, v77
	v_exp_f32_e32 v60, v60
	v_sub_f32_e32 v61, v61, v52
	v_add_f32_e32 v77, v72, v77
	v_exp_f32_e32 v61, v61
	v_sub_f32_e32 v62, v62, v52
	v_add_f32_e32 v77, v73, v77
	v_exp_f32_e32 v62, v62
	v_sub_f32_e32 v63, v63, v52
	v_add_f32_e32 v77, v59, v77
	v_exp_f32_e32 v63, v63
	v_sub_f32_e32 v64, v64, v52
	v_add_f32_e32 v77, v60, v77
	v_exp_f32_e32 v64, v64
	v_sub_f32_e32 v65, v65, v52
	v_add_f32_e32 v77, v61, v77
	v_exp_f32_e32 v65, v65
	v_sub_f32_e32 v34, v34, v52
	v_add_f32_e32 v77, v62, v77
	v_exp_f32_e32 v81, v34
	v_sub_f32_e32 v34, v35, v52
	v_add_f32_e32 v77, v63, v77
	v_exp_f32_e32 v150, v34
	v_sub_f32_e32 v34, v36, v52
	v_add_f32_e32 v77, v64, v77
	v_exp_f32_e32 v151, v34
	v_sub_f32_e32 v35, v37, v52
; __device__ __forceinline__ float shx(float v, int m, int lane) { return __builtin_bit_cast(float, __builtin_amdgcn_ds_bpermute((lane ^ m) << 2, __builtin_bit_cast(int, v))); }
; __device__ __forceinline__ float shx(float v, int m, int lane) { return __builtin_bit_cast(float, __builtin_amdgcn_ds_bpermute((lane ^ m) << 2, __builtin_bit_cast(int, v))); }
; #define MFMA32(a, b, c) __builtin_amdgcn_mfma_f32_32x32x16_bf16((a), (b), (c), 0, 0, 0)
; __device__ __forceinline__ void phase(LAS unsigned char* L, const u16* __restrict__ QKV, u16* OBg0, u16* OBg1, u16* OBg2, float* LSE, int first, int stride, const int tid) {
;     ...
;         for (int kb = 0; kb < 5; ++kb)
; #pragma unroll
;             for (int i = 0; i < 16; ++i) { X[kb][i] = __builtin_amdgcn_exp2f(X[kb][i] - m); l += X[kb][i]; }
;         l += shx(l, 32, lane);
;         f32x16 y[2]; y[0] = f32x16{}; y[1] = f32x16{};
; #pragma unroll
;         for (int kb = 0; kb < 5; ++kb) {
;             bf16x8 vf[2][2];
; #pragma unroll
;             for (int s2 = 0; s2 < 2; ++s2)
; #pragma unroll
;                 for (int dt = 0; dt < 2; ++dt) vf[s2][dt] = trfrag(L + O_V, VP, 32 * w + 32 * kb + 16 * s2 + 4 * h, 8, 32 * dt, lane);
;             const bf16x8 pb0 = pack8(X[kb], 0), pb1 = pack8(X[kb], 8);
;             y[0] = MFMA32(vf[0][0], pb0, y[0]); y[1] = MFMA32(vf[0][1], pb0, y[1]); y[0] = MFMA32(vf[1][0], pb1, y[0]); y[1] = MFMA32(vf[1][1], pb1, y[1]);
	v_add_f32_e32 v34, v65, v77
	v_exp_f32_e32 v77, v35
	v_sub_f32_e32 v35, v38, v52
	v_add_f32_e32 v34, v81, v34
	v_exp_f32_e32 v152, v35
	v_sub_f32_e32 v35, v39, v52
	v_add_f32_e32 v34, v150, v34
	v_exp_f32_e32 v153, v35
	v_sub_f32_e32 v35, v40, v52
	v_add_f32_e32 v34, v151, v34
	v_exp_f32_e32 v154, v35
	v_sub_f32_e32 v35, v41, v52
	v_add_f32_e32 v34, v77, v34
	v_exp_f32_e32 v155, v35
	v_sub_f32_e32 v35, v42, v52
	v_add_f32_e32 v34, v152, v34
	v_exp_f32_e32 v156, v35
	v_sub_f32_e32 v35, v43, v52
	v_add_f32_e32 v34, v153, v34
	v_exp_f32_e32 v157, v35
	v_sub_f32_e32 v35, v44, v52
	v_add_f32_e32 v34, v154, v34
	v_exp_f32_e32 v161, v35
	v_sub_f32_e32 v35, v45, v52
	v_add_f32_e32 v34, v155, v34
	v_exp_f32_e32 v204, v35
	v_sub_f32_e32 v35, v46, v52
	v_add_f32_e32 v34, v156, v34
	v_exp_f32_e32 v46, v35
	v_sub_f32_e32 v35, v47, v52
	v_add_f32_e32 v34, v157, v34
	v_exp_f32_e32 v47, v35
	v_sub_f32_e32 v35, v48, v52
	v_add_f32_e32 v34, v161, v34
	v_exp_f32_e32 v48, v35
	v_sub_f32_e32 v35, v49, v52
	v_add_f32_e32 v34, v204, v34
	v_exp_f32_e32 v49, v35
	v_sub_f32_e32 v18, v18, v52
	v_add_f32_e32 v34, v46, v34
	v_exp_f32_e32 v205, v18
	v_sub_f32_e32 v18, v19, v52
	v_add_f32_e32 v34, v47, v34
	v_exp_f32_e32 v206, v18
	v_sub_f32_e32 v18, v20, v52
	v_add_f32_e32 v34, v48, v34
	v_exp_f32_e32 v207, v18
	v_sub_f32_e32 v19, v21, v52
	v_add_f32_e32 v18, v49, v34
	v_exp_f32_e32 v221, v19
	v_sub_f32_e32 v19, v22, v52
	v_add_f32_e32 v18, v205, v18
	v_exp_f32_e32 v222, v19
	v_sub_f32_e32 v19, v23, v52
	v_add_f32_e32 v18, v206, v18
	v_exp_f32_e32 v223, v19
	v_sub_f32_e32 v19, v24, v52
	v_add_f32_e32 v18, v207, v18
	v_exp_f32_e32 v224, v19
	v_sub_f32_e32 v19, v25, v52
	v_add_f32_e32 v18, v221, v18
	v_exp_f32_e32 v225, v19
	v_sub_f32_e32 v19, v26, v52
	v_add_f32_e32 v18, v222, v18
	v_exp_f32_e32 v226, v19
	v_sub_f32_e32 v19, v27, v52
	v_add_f32_e32 v18, v223, v18
	v_exp_f32_e32 v227, v19
	v_sub_f32_e32 v19, v28, v52
	v_add_f32_e32 v18, v224, v18
	v_exp_f32_e32 v228, v19
	v_sub_f32_e32 v19, v29, v52
	v_add_f32_e32 v18, v225, v18
	v_exp_f32_e32 v229, v19
	v_sub_f32_e32 v19, v30, v52
	v_add_f32_e32 v18, v226, v18
	v_exp_f32_e32 v230, v19
	v_sub_f32_e32 v19, v31, v52
	v_add_f32_e32 v18, v227, v18
	v_exp_f32_e32 v231, v19
	v_sub_f32_e32 v19, v32, v52
	v_add_f32_e32 v18, v228, v18
	v_exp_f32_e32 v232, v19
	v_sub_f32_e32 v19, v33, v52
	v_add_f32_e32 v18, v229, v18
	v_exp_f32_e32 v233, v19
	v_sub_f32_e32 v2, v2, v52
	v_add_f32_e32 v18, v230, v18
	v_exp_f32_e32 v234, v2
	v_sub_f32_e32 v2, v3, v52
	v_add_f32_e32 v18, v231, v18
	v_exp_f32_e32 v235, v2
	v_sub_f32_e32 v2, v4, v52
	v_add_f32_e32 v18, v232, v18
	v_exp_f32_e32 v236, v2
	v_sub_f32_e32 v3, v5, v52
	v_add_f32_e32 v2, v233, v18
	v_exp_f32_e32 v237, v3
	v_sub_f32_e32 v3, v6, v52
	v_add_f32_e32 v2, v234, v2
	v_exp_f32_e32 v238, v3
	v_sub_f32_e32 v3, v7, v52
	v_add_f32_e32 v2, v235, v2
	v_exp_f32_e32 v239, v3
	v_sub_f32_e32 v3, v8, v52
	v_add_f32_e32 v2, v236, v2
	v_exp_f32_e32 v240, v3
	v_sub_f32_e32 v3, v9, v52
	v_add_f32_e32 v2, v237, v2
	v_exp_f32_e32 v241, v3
	v_sub_f32_e32 v3, v10, v52
	v_add_f32_e32 v2, v238, v2
	v_exp_f32_e32 v242, v3
	v_sub_f32_e32 v3, v11, v52
	v_add_f32_e32 v2, v239, v2
	v_exp_f32_e32 v243, v3
	v_sub_f32_e32 v3, v12, v52
	v_add_f32_e32 v2, v240, v2
	v_exp_f32_e32 v244, v3
	v_add_f32_e32 v2, v241, v2
	v_add_f32_e32 v2, v242, v2
	v_add_f32_e32 v2, v243, v2
	v_add_f32_e32 v6, v244, v2
	v_sub_f32_e32 v2, v13, v52
	v_exp_f32_e32 v245, v2
	v_sub_f32_e32 v2, v14, v52
	v_exp_f32_e32 v251, v2
	ds_read_b64_tr_b16 v[2:3], v200 offset:55296
	ds_read_b64_tr_b16 v[4:5], v200 offset:56832
	v_add_f32_e32 v6, v245, v6
	v_cvt_pk_bf16_f32 v10, v74, v75
	v_cvt_pk_bf16_f32 v11, v76, v78
	v_cvt_pk_bf16_f32 v12, v79, v80
	v_cvt_pk_bf16_f32 v13, v71, v72
	v_add_f32_e32 v252, v251, v6
	ds_read_b64_tr_b16 v[8:9], v200 offset:56896
	ds_read_b64_tr_b16 v[6:7], v200 offset:55360
	s_waitcnt lgkmcnt(2)
	v_mfma_f32_32x32x16_bf16 v[18:33], v[2:5], v[10:13], 0
	v_sub_f32_e32 v2, v15, v52
	ds_read_b64_tr_b16 v[34:35], v200 offset:58368
	ds_read_b64_tr_b16 v[36:37], v200 offset:59904
	v_exp_f32_e32 v71, v2
	v_sub_f32_e32 v2, v16, v52
	v_exp_f32_e32 v72, v2
	v_sub_f32_e32 v38, v17, v52
	v_exp_f32_e32 v74, v38
	s_waitcnt lgkmcnt(2)
	v_mfma_f32_32x32x16_bf16 v[2:17], v[6:9], v[10:13], 0
	v_cvt_pk_bf16_f32 v42, v73, v59
	v_cvt_pk_bf16_f32 v43, v60, v61
	v_cvt_pk_bf16_f32 v44, v62, v63
	v_cvt_pk_bf16_f32 v45, v64, v65
	ds_read_b64_tr_b16 v[40:41], v200 offset:59968
	ds_read_b64_tr_b16 v[38:39], v200 offset:58432
	v_sub_f32_e32 v63, v148, v52
	v_exp_f32_e32 v63, v63
	s_waitcnt lgkmcnt(2)
	v_mfma_f32_32x32x16_bf16 v[18:33], v[34:37], v[42:45], v[18:33]
	v_add_f32_e32 v34, v71, v252
	v_add_f32_e32 v34, v72, v34
	v_add_f32_e32 v59, v74, v34
	v_sub_f32_e32 v34, v149, v52
	v_exp_f32_e32 v60, v34
	ds_read_b64_tr_b16 v[34:35], v200 offset:61440
	ds_read_b64_tr_b16 v[36:37], v200 offset:62976
	v_sub_f32_e32 v58, v58, v52
	s_waitcnt lgkmcnt(2)
	v_mfma_f32_32x32x16_bf16 v[2:17], v[38:41], v[42:45], v[2:17]
	v_cvt_pk_bf16_f32 v42, v81, v150
	v_cvt_pk_bf16_f32 v43, v151, v77
	v_cvt_pk_bf16_f32 v44, v152, v153
	v_cvt_pk_bf16_f32 v45, v154, v155
	ds_read_b64_tr_b16 v[40:41], v200 offset:63040
	ds_read_b64_tr_b16 v[38:39], v200 offset:61504
	v_add_f32_e32 v59, v60, v59
	v_exp_f32_e32 v58, v58
	s_waitcnt lgkmcnt(2)
	v_mfma_f32_32x32x16_bf16 v[18:33], v[34:37], v[42:45], v[18:33]
	v_sub_f32_e32 v34, v146, v52
	v_exp_f32_e32 v61, v34
	v_sub_f32_e32 v34, v147, v52
	v_exp_f32_e32 v62, v34
	ds_read_b64_tr_b16 v[34:35], v200 offset:64512
	ds_read_b64_tr_b16 v[36:37], v201 offset:1536
	s_lshr_b32 s11, s11, s14
	v_lshlrev_b32_e32 v50, s9, v50
	s_waitcnt lgkmcnt(2)
; #define MFMA32(a, b, c) __builtin_amdgcn_mfma_f32_32x32x16_bf16((a), (b), (c), 0, 0, 0)
; __device__ __forceinline__ void phase(LAS unsigned char* L, const u16* __restrict__ QKV, u16* OBg0, u16* OBg1, u16* OBg2, float* LSE, int first, int stride, const int tid) {
;     ...
;         f32x16 y[2]; y[0] = f32x16{}; y[1] = f32x16{};
; #pragma unroll
;         for (int kb = 0; kb < 5; ++kb) {
;             bf16x8 vf[2][2];
; #pragma unroll
;             for (int s2 = 0; s2 < 2; ++s2)
; #pragma unroll
;                 for (int dt = 0; dt < 2; ++dt) vf[s2][dt] = trfrag(L + O_V, VP, 32 * w + 32 * kb + 16 * s2 + 4 * h, 8, 32 * dt, lane);
;             const bf16x8 pb0 = pack8(X[kb], 0), pb1 = pack8(X[kb], 8);
;             y[0] = MFMA32(vf[0][0], pb0, y[0]); y[1] = MFMA32(vf[0][1], pb0, y[1]); y[0] = MFMA32(vf[1][0], pb1, y[0]); y[1] = MFMA32(vf[1][1], pb1, y[1]);
;         }
;         const float inv = __builtin_amdgcn_rcpf(l);
;         u16* ob = (g == 0 ? OBg0 : g == 1 ? OBg1 : OBg2) + (d.rowb + qpos) * 1024 + d.hd * 64;
	v_mfma_f32_32x32x16_bf16 v[2:17], v[38:41], v[42:45], v[2:17]
	v_cvt_pk_bf16_f32 v42, v156, v157
	v_cvt_pk_bf16_f32 v43, v161, v204
	v_cvt_pk_bf16_f32 v44, v46, v47
	v_cvt_pk_bf16_f32 v45, v48, v49
	ds_read_b64_tr_b16 v[40:41], v202 offset:1536
	ds_read_b64_tr_b16 v[38:39], v200 offset:64576
	s_and_b32 s9, s68, 15
	s_lshl_b64 s[12:13], vcc, 13
	s_waitcnt lgkmcnt(2)
	v_mfma_f32_32x32x16_bf16 v[18:33], v[34:37], v[42:45], v[18:33]
	v_add_f32_e32 v34, v61, v59
	v_add_f32_e32 v34, v62, v34
	v_add_f32_e32 v46, v63, v34
	v_sub_f32_e32 v34, v70, v52
	v_exp_f32_e32 v47, v34
	ds_read_b64_tr_b16 v[34:35], v220 offset:12288
	ds_read_b64_tr_b16 v[36:37], v220 offset:13824
	v_sub_f32_e32 v59, v69, v52
	s_waitcnt lgkmcnt(2)
	v_mfma_f32_32x32x16_bf16 v[2:17], v[38:41], v[42:45], v[2:17]
	v_cvt_pk_bf16_f32 v42, v205, v206
	v_cvt_pk_bf16_f32 v43, v207, v221
	v_cvt_pk_bf16_f32 v44, v222, v223
	v_cvt_pk_bf16_f32 v45, v224, v225
	ds_read_b64_tr_b16 v[40:41], v220 offset:13888
	ds_read_b64_tr_b16 v[38:39], v220 offset:12352
	v_exp_f32_e32 v59, v59
	v_add_f32_e32 v46, v47, v46
	s_waitcnt lgkmcnt(2)
	v_mfma_f32_32x32x16_bf16 v[18:33], v[34:37], v[42:45], v[18:33]
	v_sub_f32_e32 v34, v67, v52
	v_exp_f32_e32 v48, v34
	v_sub_f32_e32 v34, v68, v52
	v_exp_f32_e32 v49, v34
	ds_read_b64_tr_b16 v[34:35], v220 offset:15360
	ds_read_b64_tr_b16 v[36:37], v220 offset:16896
	v_add_u32_e32 v50, s11, v50
	s_cmp_eq_u32 s0, 1
	s_waitcnt lgkmcnt(2)
	v_mfma_f32_32x32x16_bf16 v[2:17], v[38:41], v[42:45], v[2:17]
	v_cvt_pk_bf16_f32 v42, v226, v227
	v_cvt_pk_bf16_f32 v43, v228, v229
	v_cvt_pk_bf16_f32 v44, v230, v231
	v_cvt_pk_bf16_f32 v45, v232, v233
	ds_read_b64_tr_b16 v[40:41], v220 offset:16960
	ds_read_b64_tr_b16 v[38:39], v220 offset:15424
	v_readlane_b32 s11, v255, 1
	v_readlane_b32 s14, v255, 2
	s_waitcnt lgkmcnt(2)
	v_mfma_f32_32x32x16_bf16 v[18:33], v[34:37], v[42:45], v[18:33]
	v_add_f32_e32 v34, v48, v46
	v_add_f32_e32 v34, v49, v34
	v_add_f32_e32 v46, v59, v34
	v_sub_f32_e32 v34, v66, v52
	v_exp_f32_e32 v64, v34
	ds_read_b64_tr_b16 v[34:35], v220 offset:18432
	ds_read_b64_tr_b16 v[36:37], v220 offset:19968
	s_cselect_b32 s11, s11, s80
	s_waitcnt lgkmcnt(2)
	v_mfma_f32_32x32x16_bf16 v[2:17], v[38:41], v[42:45], v[2:17]
	v_cvt_pk_bf16_f32 v42, v234, v235
	v_cvt_pk_bf16_f32 v43, v236, v237
	v_cvt_pk_bf16_f32 v44, v238, v239
	v_cvt_pk_bf16_f32 v45, v240, v241
	ds_read_b64_tr_b16 v[40:41], v220 offset:20032
	ds_read_b64_tr_b16 v[38:39], v220 offset:18496
	v_add_f32_e32 v46, v64, v46
	s_cselect_b32 s14, s14, s81
	s_waitcnt lgkmcnt(2)
	v_mfma_f32_32x32x16_bf16 v[18:33], v[34:37], v[42:45], v[18:33]
	v_sub_f32_e32 v34, v56, v52
	v_exp_f32_e32 v56, v34
	v_sub_f32_e32 v34, v57, v52
	v_exp_f32_e32 v57, v34
	ds_read_b64_tr_b16 v[34:35], v220 offset:21504
	ds_read_b64_tr_b16 v[36:37], v220 offset:23040
	s_cmp_lt_u32 s1, 32
	v_readlane_b32 s1, v253, 58
	s_waitcnt lgkmcnt(2)
	v_mfma_f32_32x32x16_bf16 v[2:17], v[38:41], v[42:45], v[2:17]
	v_cvt_pk_bf16_f32 v42, v242, v243
	v_cvt_pk_bf16_f32 v43, v244, v245
	v_cvt_pk_bf16_f32 v44, v251, v71
	v_cvt_pk_bf16_f32 v45, v72, v74
	ds_read_b64_tr_b16 v[40:41], v220 offset:23104
	ds_read_b64_tr_b16 v[38:39], v220 offset:21568
	s_cselect_b32 s15, s1, s14
	v_readlane_b32 s1, v253, 57
	s_waitcnt lgkmcnt(2)
	v_mfma_f32_32x32x16_bf16 v[18:33], v[34:37], v[42:45], v[18:33]
	v_add_f32_e32 v34, v56, v46
	v_add_f32_e32 v34, v57, v34
	v_add_f32_e32 v46, v58, v34
	v_sub_f32_e32 v34, v55, v52
	v_exp_f32_e32 v55, v34
	ds_read_b64_tr_b16 v[34:35], v220 offset:24576
	ds_read_b64_tr_b16 v[36:37], v220 offset:26112
	s_cselect_b32 s14, s1, s11
	s_waitcnt lgkmcnt(2)
	v_mfma_f32_32x32x16_bf16 v[2:17], v[38:41], v[42:45], v[2:17]
	v_cvt_pk_bf16_f32 v42, v60, v61
	v_cvt_pk_bf16_f32 v43, v62, v63
	v_cvt_pk_bf16_f32 v44, v47, v48
	v_cvt_pk_bf16_f32 v45, v49, v59
	ds_read_b64_tr_b16 v[40:41], v220 offset:26176
	ds_read_b64_tr_b16 v[38:39], v220 offset:24640
	v_sub_f32_e32 v49, v54, v52
	v_exp_f32_e32 v49, v49
	s_waitcnt lgkmcnt(2)
; __device__ __forceinline__ unsigned pk2(float lo, float hi) { f32x2_t v = {lo, hi}; bf16x2_t b = __builtin_convertvector(v, bf16x2_t); return __builtin_bit_cast(unsigned, b); }
; #define MFMA32(a, b, c) __builtin_amdgcn_mfma_f32_32x32x16_bf16((a), (b), (c), 0, 0, 0)
; __device__ __forceinline__ void phase(LAS unsigned char* L, const u16* __restrict__ QKV, u16* OBg0, u16* OBg1, u16* OBg2, float* LSE, int first, int stride, const int tid) {
;     ...
;             y[0] = MFMA32(vf[0][0], pb0, y[0]); y[1] = MFMA32(vf[0][1], pb0, y[1]); y[0] = MFMA32(vf[1][0], pb1, y[0]); y[1] = MFMA32(vf[1][1], pb1, y[1]);
;         }
;         const float inv = __builtin_amdgcn_rcpf(l);
;         u16* ob = (g == 0 ? OBg0 : g == 1 ? OBg1 : OBg2) + (d.rowb + qpos) * 1024 + d.hd * 64;
; #pragma unroll
;         for (int dt = 0; dt < 2; ++dt)
; #pragma unroll
;             for (int gp = 0; gp < 2; ++gp) {
;                 const int ge = 2 * gp, go = 2 * gp + 1;
;                 unsigned e0 = pk2(y[dt][4 * ge] * inv, y[dt][4 * ge + 1] * inv), e1 = pk2(y[dt][4 * ge + 2] * inv, y[dt][4 * ge + 3] * inv);
;                 unsigned o0 = pk2(y[dt][4 * go] * inv, y[dt][4 * go + 1] * inv), o1 = pk2(y[dt][4 * go + 2] * inv, y[dt][4 * go + 3] * inv);
;                 const auto s0 = __builtin_amdgcn_permlane32_swap(e0, o0, false, false); const auto s1 = __builtin_amdgcn_permlane32_swap(e1, o1, false, false);
;                 const v4u wv = {s0[0], s1[0], s0[1], s1[1]};
;                 *(v4u*)(ob + 32 * dt + 8 * (2 * gp + h)) = wv; }
;         if (h == 0) LSE[((size_t)g * MTOK + d.rowb + qpos) * 16 + d.hd] = (m + __log2f(l)) * 0.6931471805599453f;
	v_mfma_f32_32x32x16_bf16 v[18:33], v[34:37], v[42:45], v[18:33]
	v_sub_f32_e32 v34, v51, v52
	v_exp_f32_e32 v47, v34
	v_sub_f32_e32 v34, v53, v52
	v_exp_f32_e32 v48, v34
	ds_read_b64_tr_b16 v[34:35], v220 offset:27648
	ds_read_b64_tr_b16 v[36:37], v220 offset:29184
	v_add_f32_e32 v46, v55, v46
	v_ashrrev_i32_e32 v51, 31, v50
	s_waitcnt lgkmcnt(2)
	v_mfma_f32_32x32x16_bf16 v[2:17], v[38:41], v[42:45], v[2:17]
	v_cvt_pk_bf16_f32 v42, v64, v56
	v_cvt_pk_bf16_f32 v43, v57, v58
	v_cvt_pk_bf16_f32 v44, v55, v47
	v_cvt_pk_bf16_f32 v45, v48, v49
	ds_read_b64_tr_b16 v[40:41], v220 offset:29248
	ds_read_b64_tr_b16 v[38:39], v220 offset:27712
	s_lshl_b32 s68, s9, 7
	s_waitcnt lgkmcnt(2)
	v_mfma_f32_32x32x16_bf16 v[18:33], v[34:37], v[42:45], v[18:33]
	v_add_f32_e32 v34, v47, v46
	v_add_f32_e32 v34, v48, v34
	v_add_f32_e32 v34, v49, v34
	ds_bpermute_b32 v35, v171, v34
	s_waitcnt lgkmcnt(0)
	v_add_f32_e32 v36, v34, v35
	v_mfma_f32_32x32x16_bf16 v[2:17], v[38:41], v[42:45], v[2:17]
	v_rcp_f32_e32 v38, v36
	v_lshl_add_u64 v[34:35], s[12:13], 0, v[50:51]
	v_lshlrev_b64 v[40:41], 11, v[34:35]
	v_lshl_add_u64 v[40:41], s[14:15], 0, v[40:41]
	s_nop 0
	v_pk_mul_f32 v[18:19], v[18:19], v[38:39] op_sel_hi:[1,0]
	v_pk_mul_f32 v[20:21], v[20:21], v[38:39] op_sel_hi:[1,0]
	v_cvt_pk_bf16_f32 v18, v18, v19
	s_nop 3
	v_pk_mul_f32 v[2:3], v[2:3], v[38:39] op_sel_hi:[1,0]
	v_pk_mul_f32 v[4:5], v[4:5], v[38:39] op_sel_hi:[1,0]
	v_cvt_pk_bf16_f32 v19, v20, v21
	v_pk_mul_f32 v[20:21], v[22:23], v[38:39] op_sel_hi:[1,0]
	v_pk_mul_f32 v[22:23], v[24:25], v[38:39] op_sel_hi:[1,0]
	v_cvt_pk_bf16_f32 v2, v2, v3
	v_cvt_pk_bf16_f32 v3, v4, v5
	v_pk_mul_f32 v[4:5], v[6:7], v[38:39] op_sel_hi:[1,0]
	v_pk_mul_f32 v[6:7], v[8:9], v[38:39] op_sel_hi:[1,0]
	v_lshl_add_u64 v[40:41], v[40:41], 0, s[68:69]
	v_cvt_pk_bf16_f32 v20, v20, v21
	v_cvt_pk_bf16_f32 v21, v22, v23
	v_cvt_pk_bf16_f32 v4, v4, v5
	v_cvt_pk_bf16_f32 v5, v6, v7
	v_permlane32_swap_b32_e32 v18, v20
	v_permlane32_swap_b32_e32 v19, v21
	v_lshl_add_u64 v[22:23], v[40:41], 0, v[0:1]
	v_permlane32_swap_b32_e32 v2, v4
	v_permlane32_swap_b32_e32 v3, v5
	global_store_dwordx4 v[22:23], v[18:21], off
	global_store_dwordx4 v[22:23], v[2:5], off offset:64
	v_pk_mul_f32 v[24:25], v[32:33], v[38:39] op_sel_hi:[1,0]
	v_pk_mul_f32 v[18:19], v[26:27], v[38:39] op_sel_hi:[1,0]
	v_pk_mul_f32 v[20:21], v[28:29], v[38:39] op_sel_hi:[1,0]
	v_pk_mul_f32 v[2:3], v[10:11], v[38:39] op_sel_hi:[1,0]
	v_pk_mul_f32 v[4:5], v[12:13], v[38:39] op_sel_hi:[1,0]
	v_cvt_pk_bf16_f32 v18, v18, v19
	v_cvt_pk_bf16_f32 v19, v20, v21
	v_pk_mul_f32 v[20:21], v[30:31], v[38:39] op_sel_hi:[1,0]
	v_cvt_pk_bf16_f32 v2, v2, v3
	v_cvt_pk_bf16_f32 v3, v4, v5
	v_pk_mul_f32 v[4:5], v[14:15], v[38:39] op_sel_hi:[1,0]
	v_pk_mul_f32 v[6:7], v[16:17], v[38:39] op_sel_hi:[1,0]
	v_cvt_pk_bf16_f32 v20, v20, v21
	v_cvt_pk_bf16_f32 v21, v24, v25
	v_cvt_pk_bf16_f32 v4, v4, v5
	v_cvt_pk_bf16_f32 v5, v6, v7
	v_permlane32_swap_b32_e32 v18, v20
	v_permlane32_swap_b32_e32 v19, v21
	v_permlane32_swap_b32_e32 v2, v4
	v_permlane32_swap_b32_e32 v3, v5
	global_store_dwordx4 v[22:23], v[18:21], off offset:32
	global_store_dwordx4 v[22:23], v[2:5], off offset:96
	s_and_saveexec_b64 vcc, s[88:89]
	s_cbranch_execz .LBB0_471
	v_log_f32_e32 v2, v36
	s_ashr_i32 s1, s0, 31
	s_lshl_b64 s[0:1], s[0:1], 15
	s_lshl_b32 s68, s9, 2
	v_add_f32_e32 v2, v52, v2
	v_mul_f32_e32 v4, 0x3f317218, v2
	v_lshl_add_u64 v[2:3], v[34:35], 0, s[0:1]
	v_readlane_b32 s0, v253, 63
	v_lshlrev_b64 v[2:3], 6, v[2:3]
	v_readlane_b32 s1, v255, 0
	s_nop 1
	v_lshl_add_u64 v[2:3], s[0:1], 0, v[2:3]
	v_lshl_add_u64 v[2:3], v[2:3], 0, s[68:69]
	global_store_dword v[2:3], v4, off
	s_branch .LBB0_471
